# MoBA own-block epilogue: partial-output loads widened to 12 dwordx4 + permlane32_swap un-shuffle, output stores widened to 4 dwordx4; plus widened selected-block partial stores
# speedup vs baseline: 1.0122x; 1.0094x over previous
; __device__ __forceinline__ unsigned cvt_pk_bf16(float lo, float hi) { f32x2_t v = {lo, hi}; bf16x2_t b = __builtin_convertvector(v, bf16x2_t); return __builtin_bit_cast(unsigned, b); }
; __device__ __forceinline__ float bf_lo(unsigned w) { return __uint_as_float(w << 16); }
; __device__ __forceinline__ float bf_hi(unsigned w) { return __uint_as_float(w & 0xffff0000u); }
; __device__ __forceinline__ void moba_own_unit(LAS char* lds, int bh, int jblk, const bf16_t* H, const bf16_t* PO, const float* PML, bf16_t* U, int tid) {
;     ...
; #pragma unroll
;     for (int d0 = 0; d0 < 2; ++d0)
; #pragma unroll
;         for (int g = 0; g < 4; ++g) { const int d = 32 * d0 + 8 * g + 4 * hh; const f32x16& o = d0 ? o1 : o0;
;             float a0 = o[4 * g] * wown, a1 = o[4 * g + 1] * wown, a2 = o[4 * g + 2] * wown, a3 = o[4 * g + 3] * wown;
; #pragma unroll
;             for (int s = 0; s < 3; ++s) if (s < nsel) { const u32x2 pv = *(const u32x2*)(PO + (pidx + s) * 64 + d); a0 += wi[s] * bf_lo(pv.x); a1 += wi[s] * bf_hi(pv.x); a2 += wi[s] * bf_lo(pv.y); a3 += wi[s] * bf_hi(pv.y); }
;             const u32x2 z = zr.z[d0][g];
;             u32x2 w; w.x = cvt_pk_bf16(a0 * inv * bf_lo(z.x), a1 * inv * bf_hi(z.x)); w.y = cvt_pk_bf16(a2 * inv * bf_lo(z.y), a3 * inv * bf_hi(z.y));
;             *(u32x2*)(urow + d) = w; }
.LBB0_631:
	v_mul_f32_e32 v4, v34, v4
	v_mul_f32_e32 v5, v35, v5
	v_lshlrev_b32_e32 v6, 16, v120
	v_and_b32_e32 v7, 0xffff0000, v120
	v_mul_f32_e32 v4, v4, v6
	v_mul_f32_e32 v5, v5, v7
	v_mul_f32_e32 v2, v34, v2
	v_mul_f32_e32 v3, v35, v3
	v_lshlrev_b32_e32 v6, 16, v121
	v_and_b32_e32 v7, 0xffff0000, v121
	v_mul_f32_e32 v2, v2, v6
	v_mul_f32_e32 v3, v3, v7
	s_add_i32 s23, s23, s56
	v_cvt_pk_bf16_f32 v4, v4, v5
	v_cvt_pk_bf16_f32 v5, v2, v3
	s_cmpk_gt_i32 s23, 0x3ff
	v_mov_b32_e32 v86, v4
	v_mov_b32_e32 v87, v5
	v_mbcnt_lo_u32_b32 v160, -1, 0
	v_mbcnt_hi_u32_b32 v160, -1, v160
	v_and_b32_e32 v160, 32, v160
	v_lshrrev_b32_e32 v160, 2, v160
	v_mov_b32_e32 v161, 0
	v_lshl_add_u64 v[158:159], v[22:23], 0, v[160:161]
	v_permlane32_swap_b32_e32 v48, v50
	v_permlane32_swap_b32_e32 v49, v51
	global_store_dwordx4 v[158:159], v[48:51], off
	v_permlane32_swap_b32_e32 v60, v62
	v_permlane32_swap_b32_e32 v61, v63
	global_store_dwordx4 v[158:159], v[60:63], off offset:32
	v_permlane32_swap_b32_e32 v72, v74
	v_permlane32_swap_b32_e32 v73, v75
	global_store_dwordx4 v[158:159], v[72:75], off offset:64
	v_permlane32_swap_b32_e32 v84, v86
	v_permlane32_swap_b32_e32 v85, v87
	global_store_dwordx4 v[158:159], v[84:87], off offset:96
	s_cbranch_scc1 .LBB0_773

; __device__ __forceinline__ unsigned cvt_pk_bf16(float lo, float hi) { f32x2_t v = {lo, hi}; bf16x2_t b = __builtin_convertvector(v, bf16x2_t); return __builtin_bit_cast(unsigned, b); }
; __device__ __forceinline__ float bf_lo(unsigned w) { return __uint_as_float(w << 16); }
; __device__ __forceinline__ float bf_hi(unsigned w) { return __uint_as_float(w & 0xffff0000u); }
; __device__ __forceinline__ float fast_exp2(float x) { return __builtin_amdgcn_exp2f(x); }
; __device__ __forceinline__ float fast_rcp(float x) { return __builtin_amdgcn_rcpf(x); }
; __device__ __forceinline__ float swap_sum(float v) { auto rr = __builtin_amdgcn_permlane32_swap(__float_as_uint(v), __float_as_uint(v), false, false); return __uint_as_float(rr[0]) + __uint_as_float(rr[1]); }
; __device__ __forceinline__ void moba_own_unit(LAS char* lds, int bh, int jblk, const bf16_t* H, const bf16_t* PO, const float* PML, bf16_t* U, int tid) {
;     ...
;     const float lt = swap_sum(l);
;     const float mown = m - slope2 * (float)(qpos - s0);
;     float M = mown;
; #pragma unroll
;     for (int s = 0; s < 3; ++s) if (s < nsel) M = fmaxf(M, mi[s]);
;     const float wown = fast_exp2(mown - M); float den = wown * lt;
; #pragma unroll
;     for (int s = 0; s < 3; ++s) { wi[s] = (s < nsel) ? wi[s] * fast_exp2(mi[s] - M) : 0.f; den += wi[s]; }
;     const float inv = fast_rcp(den);
;     bf16_t* urow = U + ((size_t)b * SEQ + qpos) * 2048 + U_MOBA + h * 64;
; #pragma unroll
;     for (int d0 = 0; d0 < 2; ++d0)
; #pragma unroll
;         for (int g = 0; g < 4; ++g) { const int d = 32 * d0 + 8 * g + 4 * hh; const f32x16& o = d0 ? o1 : o0;
;             float a0 = o[4 * g] * wown, a1 = o[4 * g + 1] * wown, a2 = o[4 * g + 2] * wown, a3 = o[4 * g + 3] * wown;
; #pragma unroll
;             for (int s = 0; s < 3; ++s) if (s < nsel) { const u32x2 pv = *(const u32x2*)(PO + (pidx + s) * 64 + d); a0 += wi[s] * bf_lo(pv.x); a1 += wi[s] * bf_hi(pv.x); a2 += wi[s] * bf_lo(pv.y); a3 += wi[s] * bf_hi(pv.y); }
;             const u32x2 z = zr.z[d0][g];
;             u32x2 w; w.x = cvt_pk_bf16(a0 * inv * bf_lo(z.x), a1 * inv * bf_hi(z.x)); w.y = cvt_pk_bf16(a2 * inv * bf_lo(z.y), a3 * inv * bf_hi(z.y));
.LBB0_725:
	v_subrev_u32_e32 v36, s24, v144
	v_cvt_f32_i32_e32 v36, v36
	v_max_f32_e32 v37, v146, v146
	v_max_f32_e32 v38, v140, v140
	s_waitcnt lgkmcnt(0)
	s_barrier
	v_fma_f32 v36, -v148, v36, v122
	v_max_f32_e32 v37, v36, v37
	v_cndmask_b32_e64 v37, v36, v37, s[40:41]
	v_max_f32_e32 v38, v37, v38
	v_cndmask_b32_e64 v37, v37, v38, s[42:43]
	v_max_f32_e32 v38, v142, v142
	v_max_f32_e32 v38, v37, v38
	v_cndmask_b32_e64 v37, v37, v38, s[44:45]
	v_sub_f32_e32 v36, v36, v37
	v_exp_f32_e32 v38, v36
	v_sub_f32_e32 v36, v146, v37
	v_exp_f32_e32 v36, v36
	v_mov_b32_e32 v35, v34
	s_nop 1
	v_permlane32_swap_b32_e32 v34, v35
	v_mul_f32_e32 v36, v147, v36
	v_mul_f32_e32 v42, v18, v38
	v_mul_f32_e32 v43, v19, v38
	v_mul_f32_e32 v40, v20, v38
	v_mul_f32_e32 v41, v21, v38
	s_and_b64 vcc, exec, s[40:41]
	s_cbranch_vccz .Lown_pf_done
	v_mbcnt_lo_u32_b32 v160, -1, 0
	v_mbcnt_hi_u32_b32 v160, -1, v160
	v_and_b32_e32 v160, 32, v160
	v_lshrrev_b32_e32 v160, 2, v160
	v_mov_b32_e32 v161, 0
	v_mad_u64_u32 v[96:97], s[4:5], v145, s10, v[102:103]
	v_mov_b32_e32 v98, v97
	v_mad_u64_u32 v[98:99], s[4:5], v123, s10, v[98:99]
	v_mov_b32_e32 v150, v96
	v_mov_b32_e32 v151, v98
	v_lshl_add_u64 v[150:151], v[150:151], 0, v[160:161]
	v_mad_u64_u32 v[96:97], s[4:5], v145, s10, v[106:107]
	v_mov_b32_e32 v98, v97
	v_mad_u64_u32 v[98:99], s[4:5], v123, s10, v[98:99]
	v_mov_b32_e32 v152, v96
	v_mov_b32_e32 v153, v98
	v_lshl_add_u64 v[152:153], v[152:153], 0, v[160:161]
	v_mad_u64_u32 v[96:97], s[4:5], v145, s10, v[110:111]
	v_mov_b32_e32 v98, v97
	v_mad_u64_u32 v[98:99], s[4:5], v123, s10, v[98:99]
	v_mov_b32_e32 v154, v96
	v_mov_b32_e32 v155, v98
	v_lshl_add_u64 v[154:155], v[154:155], 0, v[160:161]
	v_mad_u64_u32 v[96:97], s[4:5], v145, s10, v[114:115]
	v_mov_b32_e32 v98, v97
	v_mad_u64_u32 v[98:99], s[4:5], v123, s10, v[98:99]
	v_mov_b32_e32 v156, v96
	v_mov_b32_e32 v157, v98
	v_lshl_add_u64 v[156:157], v[156:157], 0, v[160:161]
	global_load_dwordx4 v[48:51], v[150:151], off
	global_load_dwordx4 v[60:63], v[152:153], off
	global_load_dwordx4 v[72:75], v[154:155], off
	global_load_dwordx4 v[84:87], v[156:157], off
	s_and_b64 vcc, exec, s[42:43]
	s_cbranch_vccz .Lown_pf_done
	global_load_dwordx4 v[52:55], v[150:151], off offset:128
	global_load_dwordx4 v[64:67], v[152:153], off offset:128
	global_load_dwordx4 v[76:79], v[154:155], off offset:128
	global_load_dwordx4 v[88:91], v[156:157], off offset:128
	s_and_b64 vcc, exec, s[44:45]
	s_cbranch_vccz .Lown_pf_done
	global_load_dwordx4 v[56:59], v[150:151], off offset:256
	global_load_dwordx4 v[68:71], v[152:153], off offset:256
	global_load_dwordx4 v[80:83], v[154:155], off offset:256
	global_load_dwordx4 v[92:95], v[156:157], off offset:256
.Lown_pf_done:
	s_and_b64 vcc, exec, s[40:41]
	s_cbranch_vccz .LBB0_727
	s_waitcnt vmcnt(0)
	v_permlane32_swap_b32_e32 v48, v50
	v_permlane32_swap_b32_e32 v49, v51
	v_permlane32_swap_b32_e32 v52, v54
	v_permlane32_swap_b32_e32 v53, v55
	v_permlane32_swap_b32_e32 v56, v58
	v_permlane32_swap_b32_e32 v57, v59
	v_permlane32_swap_b32_e32 v60, v62
	v_permlane32_swap_b32_e32 v61, v63
	v_permlane32_swap_b32_e32 v64, v66
	v_permlane32_swap_b32_e32 v65, v67
	v_permlane32_swap_b32_e32 v68, v70
	v_permlane32_swap_b32_e32 v69, v71
	v_permlane32_swap_b32_e32 v72, v74
	v_permlane32_swap_b32_e32 v73, v75
	v_permlane32_swap_b32_e32 v76, v78
	v_permlane32_swap_b32_e32 v77, v79
	v_permlane32_swap_b32_e32 v80, v82
	v_permlane32_swap_b32_e32 v81, v83
	v_permlane32_swap_b32_e32 v84, v86
	v_permlane32_swap_b32_e32 v85, v87
	v_permlane32_swap_b32_e32 v88, v90
	v_permlane32_swap_b32_e32 v89, v91
	v_permlane32_swap_b32_e32 v92, v94
	v_permlane32_swap_b32_e32 v93, v95
	v_mov_b32_e32 v18, v48
	v_mov_b32_e32 v19, v49
	v_lshlrev_b32_e32 v20, 16, v18
	v_and_b32_e32 v21, 0xffff0000, v18
	v_lshlrev_b32_e32 v18, 16, v19
	v_and_b32_e32 v19, 0xffff0000, v19
	v_fma_f32 v42, v36, v20, v42
	v_fma_f32 v43, v36, v21, v43
	v_fma_f32 v40, v36, v18, v40
	v_fma_f32 v41, v36, v19, v41
.LBB0_727:
	v_sub_f32_e32 v18, v140, v37
	v_exp_f32_e32 v18, v18
	v_cndmask_b32_e64 v19, 0, 1, s[42:43]
	v_cmp_ne_u32_e64 s[46:47], 1, v19
	s_andn2_b64 vcc, exec, s[42:43]
	v_mul_f32_e32 v18, v141, v18
	s_cbranch_vccnz .LBB0_729
	v_mov_b32_e32 v20, v52
	v_mov_b32_e32 v21, v53
	v_lshlrev_b32_e32 v44, 16, v20
	v_and_b32_e32 v45, 0xffff0000, v20
	v_lshlrev_b32_e32 v20, 16, v21
	v_and_b32_e32 v21, 0xffff0000, v21
	v_fma_f32 v42, v18, v44, v42
	v_fma_f32 v43, v18, v45, v43
	v_fma_f32 v40, v18, v20, v40
	v_fma_f32 v41, v18, v21, v41
.LBB0_729:
	v_sub_f32_e32 v19, v142, v37
	v_exp_f32_e32 v19, v19
	v_cndmask_b32_e64 v20, 0, 1, s[44:45]
	v_cmp_ne_u32_e64 s[48:49], 1, v20
	s_andn2_b64 vcc, exec, s[44:45]
	v_mul_f32_e32 v20, v143, v19
	s_cbranch_vccnz .LBB0_731
	v_mov_b32_e32 v44, v56
	v_mov_b32_e32 v45, v57
	v_lshlrev_b32_e32 v46, 16, v44
	v_and_b32_e32 v47, 0xffff0000, v44
	v_lshlrev_b32_e32 v44, 16, v45
	v_and_b32_e32 v45, 0xffff0000, v45
	v_fma_f32 v42, v20, v46, v42
	v_fma_f32 v43, v20, v47, v43
	v_fma_f32 v40, v20, v44, v40
	v_fma_f32 v41, v20, v45, v41
.LBB0_731:
	v_add_f32_e32 v19, v34, v35
	v_cndmask_b32_e64 v21, 0, v36, s[40:41]
	v_fmac_f32_e32 v21, v38, v19
	v_cndmask_b32_e64 v19, 0, v18, s[42:43]
	v_add_f32_e32 v19, v19, v21
	v_cndmask_b32_e64 v21, 0, v20, s[44:45]
	v_add_f32_e32 v19, v21, v19
	v_rcp_f32_e32 v34, v19
	v_lshlrev_b64 v[44:45], 12, v[138:139]
	v_lshlrev_b32_e32 v46, 16, v136
	v_and_b32_e32 v47, 0xffff0000, v136
	v_mul_f32_e32 v42, v34, v42
	v_mul_f32_e32 v43, v34, v43
	v_lshl_add_u64 v[44:45], s[0:1], 0, v[44:45]
	v_mul_f32_e32 v42, v42, v46
	v_mul_f32_e32 v43, v43, v47
	v_mul_f32_e32 v40, v34, v40
	v_mul_f32_e32 v41, v34, v41
	v_lshlrev_b32_e32 v46, 16, v137
	v_and_b32_e32 v47, 0xffff0000, v137
	v_lshl_add_u64 v[44:45], v[44:45], 0, s[30:31]
	v_mul_f32_e32 v40, v40, v46
	v_mul_f32_e32 v41, v41, v47
	v_mov_b32_e32 v119, v1
	v_cvt_pk_bf16_f32 v42, v42, v43
	v_cvt_pk_bf16_f32 v43, v40, v41
	v_lshl_add_u64 v[40:41], v[44:45], 0, v[118:119]
	v_add_co_u32_e32 v44, vcc, 0x10200000, v40
	v_mov_b32_e32 v39, v38
	s_nop 0
	v_addc_co_u32_e32 v45, vcc, 0, v41, vcc
	v_cndmask_b32_e64 v19, 0, 1, s[40:41]
	v_mov_b32_e32 v48, v42
	v_mov_b32_e32 v49, v43
	v_mul_f32_e32 v42, v22, v38
	v_mul_f32_e32 v43, v23, v39
	v_cmp_ne_u32_e64 s[42:43], 1, v19
	s_andn2_b64 vcc, exec, s[40:41]
	v_mul_f32_e32 v24, v24, v38
	v_mul_f32_e32 v25, v25, v39
	s_cbranch_vccnz .LBB0_733
	v_mov_b32_e32 v22, v50
	v_mov_b32_e32 v23, v51
	v_lshlrev_b32_e32 v44, 16, v22
	v_and_b32_e32 v45, 0xffff0000, v22
	v_lshlrev_b32_e32 v22, 16, v23
	v_and_b32_e32 v23, 0xffff0000, v23
	v_fma_f32 v42, v36, v44, v42
	v_fma_f32 v43, v36, v45, v43
	v_fma_f32 v24, v36, v22, v24
	v_fma_f32 v25, v36, v23, v25
.LBB0_733:
	s_and_b64 vcc, exec, s[46:47]
	s_cbranch_vccnz .LBB0_735
	v_mov_b32_e32 v22, v54
	v_mov_b32_e32 v23, v55
	v_lshlrev_b32_e32 v44, 16, v22
	v_and_b32_e32 v45, 0xffff0000, v22
	v_lshlrev_b32_e32 v22, 16, v23
	v_and_b32_e32 v23, 0xffff0000, v23
	v_fma_f32 v42, v18, v44, v42
	v_fma_f32 v43, v18, v45, v43
	v_fma_f32 v24, v18, v22, v24
	v_fma_f32 v25, v18, v23, v25

; __device__ __forceinline__ unsigned cvt_pk_bf16(float lo, float hi) { f32x2_t v = {lo, hi}; bf16x2_t b = __builtin_convertvector(v, bf16x2_t); return __builtin_bit_cast(unsigned, b); }
; __device__ __forceinline__ float bf_lo(unsigned w) { return __uint_as_float(w << 16); }
; __device__ __forceinline__ float bf_hi(unsigned w) { return __uint_as_float(w & 0xffff0000u); }
; __device__ __forceinline__ void moba_own_unit(LAS char* lds, int bh, int jblk, const bf16_t* H, const bf16_t* PO, const float* PML, bf16_t* U, int tid) {
;     ...
; #pragma unroll
;     for (int d0 = 0; d0 < 2; ++d0)
; #pragma unroll
;         for (int g = 0; g < 4; ++g) { const int d = 32 * d0 + 8 * g + 4 * hh; const f32x16& o = d0 ? o1 : o0;
;             float a0 = o[4 * g] * wown, a1 = o[4 * g + 1] * wown, a2 = o[4 * g + 2] * wown, a3 = o[4 * g + 3] * wown;
; #pragma unroll
;             for (int s = 0; s < 3; ++s) if (s < nsel) { const u32x2 pv = *(const u32x2*)(PO + (pidx + s) * 64 + d); a0 += wi[s] * bf_lo(pv.x); a1 += wi[s] * bf_hi(pv.x); a2 += wi[s] * bf_lo(pv.y); a3 += wi[s] * bf_hi(pv.y); }
;             const u32x2 z = zr.z[d0][g];
;             u32x2 w; w.x = cvt_pk_bf16(a0 * inv * bf_lo(z.x), a1 * inv * bf_hi(z.x)); w.y = cvt_pk_bf16(a2 * inv * bf_lo(z.y), a3 * inv * bf_hi(z.y));
;             *(u32x2*)(urow + d) = w; }
.LBB0_737:
	v_mov_b32_e32 v35, v34
	s_mov_b64 s[4:5], 0x10200800
	v_lshl_add_u64 v[22:23], v[40:41], 0, s[4:5]
	v_mul_f32_e32 v40, v34, v42
	v_mul_f32_e32 v41, v35, v43
	v_lshlrev_b32_e32 v42, 16, v134
	v_and_b32_e32 v43, 0xffff0000, v134
	v_mul_f32_e32 v40, v40, v42
	v_mul_f32_e32 v41, v41, v43
	v_mul_f32_e32 v24, v34, v24
	v_mul_f32_e32 v25, v35, v25
	v_lshlrev_b32_e32 v42, 16, v135
	v_and_b32_e32 v43, 0xffff0000, v135
	v_mul_f32_e32 v24, v24, v42
	v_mul_f32_e32 v25, v25, v43
	v_cvt_pk_bf16_f32 v40, v40, v41
	v_cvt_pk_bf16_f32 v41, v24, v25
	v_mul_f32_e32 v26, v26, v38
	v_mul_f32_e32 v27, v27, v39
	s_and_b64 vcc, exec, s[42:43]
	v_mul_f32_e32 v24, v28, v38
	v_mul_f32_e32 v25, v29, v39
	v_mov_b32_e32 v50, v40
	v_mov_b32_e32 v51, v41
	s_cbranch_vccnz .LBB0_739
	v_mov_b32_e32 v28, v60
	v_mov_b32_e32 v29, v61
	v_lshlrev_b32_e32 v40, 16, v28
	v_and_b32_e32 v41, 0xffff0000, v28
	v_lshlrev_b32_e32 v28, 16, v29
	v_and_b32_e32 v29, 0xffff0000, v29
	v_fma_f32 v26, v36, v40, v26
	v_fma_f32 v27, v36, v41, v27
	v_fma_f32 v24, v36, v28, v24
	v_fma_f32 v25, v36, v29, v25
.LBB0_739:
	s_and_b64 vcc, exec, s[46:47]
	s_cbranch_vccnz .LBB0_741
	v_mov_b32_e32 v28, v64
	v_mov_b32_e32 v29, v65
	v_lshlrev_b32_e32 v40, 16, v28
	v_and_b32_e32 v41, 0xffff0000, v28
	v_lshlrev_b32_e32 v28, 16, v29
	v_and_b32_e32 v29, 0xffff0000, v29
	v_fma_f32 v26, v18, v40, v26
	v_fma_f32 v27, v18, v41, v27
	v_fma_f32 v24, v18, v28, v24
	v_fma_f32 v25, v18, v29, v25
.LBB0_741:
	s_and_b64 vcc, exec, s[48:49]
	s_cbranch_vccnz .LBB0_743
	v_mov_b32_e32 v28, v68
	v_mov_b32_e32 v29, v69
	v_lshlrev_b32_e32 v40, 16, v28
	v_and_b32_e32 v41, 0xffff0000, v28
	v_lshlrev_b32_e32 v28, 16, v29
	v_and_b32_e32 v29, 0xffff0000, v29
	v_fma_f32 v26, v20, v40, v26
	v_fma_f32 v27, v20, v41, v27
	v_fma_f32 v24, v20, v28, v24
	v_fma_f32 v25, v20, v29, v25
.LBB0_743:
	v_mul_f32_e32 v26, v34, v26
	v_mul_f32_e32 v27, v35, v27
	v_lshlrev_b32_e32 v28, 16, v132
	v_and_b32_e32 v29, 0xffff0000, v132
	v_mul_f32_e32 v26, v26, v28
	v_mul_f32_e32 v27, v27, v29
	v_mul_f32_e32 v24, v34, v24
	v_mul_f32_e32 v25, v35, v25
	v_lshlrev_b32_e32 v28, 16, v133
	v_and_b32_e32 v29, 0xffff0000, v133
	v_mul_f32_e32 v24, v24, v28
	v_mul_f32_e32 v25, v25, v29
	v_cvt_pk_bf16_f32 v26, v26, v27
	v_cvt_pk_bf16_f32 v27, v24, v25
	v_mov_b32_e32 v60, v26
	v_mov_b32_e32 v61, v27
	v_mul_f32_e32 v26, v30, v38
	v_mul_f32_e32 v27, v31, v39
	s_and_b64 vcc, exec, s[42:43]
	v_mul_f32_e32 v24, v32, v38
	v_mul_f32_e32 v25, v33, v39
	s_cbranch_vccnz .LBB0_745
	v_mov_b32_e32 v28, v62
	v_mov_b32_e32 v29, v63
	v_lshlrev_b32_e32 v30, 16, v28
	v_and_b32_e32 v31, 0xffff0000, v28
	v_lshlrev_b32_e32 v28, 16, v29
	v_and_b32_e32 v29, 0xffff0000, v29
	v_fma_f32 v26, v36, v30, v26
	v_fma_f32 v27, v36, v31, v27
	v_fma_f32 v24, v36, v28, v24
	v_fma_f32 v25, v36, v29, v25
.LBB0_745:
	s_and_b64 vcc, exec, s[46:47]
	s_cbranch_vccnz .LBB0_747
	v_mov_b32_e32 v28, v66
	v_mov_b32_e32 v29, v67
	v_lshlrev_b32_e32 v30, 16, v28
	v_and_b32_e32 v31, 0xffff0000, v28
	v_lshlrev_b32_e32 v28, 16, v29
	v_and_b32_e32 v29, 0xffff0000, v29
	v_fma_f32 v26, v18, v30, v26
	v_fma_f32 v27, v18, v31, v27
	v_fma_f32 v24, v18, v28, v24
	v_fma_f32 v25, v18, v29, v25

; __device__ __forceinline__ unsigned cvt_pk_bf16(float lo, float hi) { f32x2_t v = {lo, hi}; bf16x2_t b = __builtin_convertvector(v, bf16x2_t); return __builtin_bit_cast(unsigned, b); }
; __device__ __forceinline__ float bf_lo(unsigned w) { return __uint_as_float(w << 16); }
; __device__ __forceinline__ float bf_hi(unsigned w) { return __uint_as_float(w & 0xffff0000u); }
; __device__ __forceinline__ void moba_own_unit(LAS char* lds, int bh, int jblk, const bf16_t* H, const bf16_t* PO, const float* PML, bf16_t* U, int tid) {
;     ...
; #pragma unroll
;     for (int d0 = 0; d0 < 2; ++d0)
; #pragma unroll
;         for (int g = 0; g < 4; ++g) { const int d = 32 * d0 + 8 * g + 4 * hh; const f32x16& o = d0 ? o1 : o0;
;             float a0 = o[4 * g] * wown, a1 = o[4 * g + 1] * wown, a2 = o[4 * g + 2] * wown, a3 = o[4 * g + 3] * wown;
; #pragma unroll
;             for (int s = 0; s < 3; ++s) if (s < nsel) { const u32x2 pv = *(const u32x2*)(PO + (pidx + s) * 64 + d); a0 += wi[s] * bf_lo(pv.x); a1 += wi[s] * bf_hi(pv.x); a2 += wi[s] * bf_lo(pv.y); a3 += wi[s] * bf_hi(pv.y); }
;             const u32x2 z = zr.z[d0][g];
;             u32x2 w; w.x = cvt_pk_bf16(a0 * inv * bf_lo(z.x), a1 * inv * bf_hi(z.x)); w.y = cvt_pk_bf16(a2 * inv * bf_lo(z.y), a3 * inv * bf_hi(z.y));
;             *(u32x2*)(urow + d) = w; }
.LBB0_749:
	v_mul_f32_e32 v26, v34, v26
	v_mul_f32_e32 v27, v35, v27
	v_lshlrev_b32_e32 v28, 16, v130
	v_and_b32_e32 v29, 0xffff0000, v130
	v_mul_f32_e32 v26, v26, v28
	v_mul_f32_e32 v27, v27, v29
	v_mul_f32_e32 v24, v34, v24
	v_mul_f32_e32 v25, v35, v25
	v_lshlrev_b32_e32 v28, 16, v131
	v_and_b32_e32 v29, 0xffff0000, v131
	v_mul_f32_e32 v24, v24, v28
	v_mul_f32_e32 v25, v25, v29
	v_cvt_pk_bf16_f32 v26, v26, v27
	v_cvt_pk_bf16_f32 v27, v24, v25
	v_mul_f32_e32 v24, v2, v38
	v_mul_f32_e32 v25, v3, v39
	s_and_b64 vcc, exec, s[42:43]
	v_mul_f32_e32 v2, v4, v38
	v_mul_f32_e32 v3, v5, v39
	v_mov_b32_e32 v62, v26
	v_mov_b32_e32 v63, v27
	s_cbranch_vccnz .LBB0_751
	v_mov_b32_e32 v4, v72
	v_mov_b32_e32 v5, v73
	v_lshlrev_b32_e32 v26, 16, v4
	v_and_b32_e32 v27, 0xffff0000, v4
	v_lshlrev_b32_e32 v4, 16, v5
	v_and_b32_e32 v5, 0xffff0000, v5
	v_fma_f32 v24, v36, v26, v24
	v_fma_f32 v25, v36, v27, v25
	v_fma_f32 v2, v36, v4, v2
	v_fma_f32 v3, v36, v5, v3
.LBB0_751:
	s_and_b64 vcc, exec, s[46:47]
	s_cbranch_vccnz .LBB0_753
	v_mov_b32_e32 v4, v76
	v_mov_b32_e32 v5, v77
	v_lshlrev_b32_e32 v26, 16, v4
	v_and_b32_e32 v27, 0xffff0000, v4
	v_lshlrev_b32_e32 v4, 16, v5
	v_and_b32_e32 v5, 0xffff0000, v5
	v_fma_f32 v24, v18, v26, v24
	v_fma_f32 v25, v18, v27, v25
	v_fma_f32 v2, v18, v4, v2
	v_fma_f32 v3, v18, v5, v3
.LBB0_753:
	s_and_b64 vcc, exec, s[48:49]
	s_cbranch_vccnz .LBB0_755
	v_mov_b32_e32 v4, v80
	v_mov_b32_e32 v5, v81
	v_lshlrev_b32_e32 v26, 16, v4
	v_and_b32_e32 v27, 0xffff0000, v4
	v_lshlrev_b32_e32 v4, 16, v5
	v_and_b32_e32 v5, 0xffff0000, v5
	v_fma_f32 v24, v20, v26, v24
	v_fma_f32 v25, v20, v27, v25
	v_fma_f32 v2, v20, v4, v2
	v_fma_f32 v3, v20, v5, v3
.LBB0_755:
	v_mul_f32_e32 v4, v34, v24
	v_mul_f32_e32 v5, v35, v25
	v_lshlrev_b32_e32 v24, 16, v128
	v_and_b32_e32 v25, 0xffff0000, v128
	v_mul_f32_e32 v4, v4, v24
	v_mul_f32_e32 v5, v5, v25
	v_mul_f32_e32 v2, v34, v2
	v_mul_f32_e32 v3, v35, v3
	v_lshlrev_b32_e32 v24, 16, v129
	v_and_b32_e32 v25, 0xffff0000, v129
	v_mul_f32_e32 v2, v2, v24
	v_mul_f32_e32 v3, v3, v25
	v_cvt_pk_bf16_f32 v4, v4, v5
	v_cvt_pk_bf16_f32 v5, v2, v3
	v_mov_b32_e32 v72, v4
	v_mov_b32_e32 v73, v5
	v_mul_f32_e32 v4, v6, v38
	v_mul_f32_e32 v5, v7, v39
	s_and_b64 vcc, exec, s[42:43]
	v_mul_f32_e32 v2, v8, v38
	v_mul_f32_e32 v3, v9, v39
	s_cbranch_vccnz .LBB0_757
	v_mov_b32_e32 v6, v74
	v_mov_b32_e32 v7, v75
	v_lshlrev_b32_e32 v8, 16, v6
	v_and_b32_e32 v9, 0xffff0000, v6
	v_lshlrev_b32_e32 v6, 16, v7
	v_and_b32_e32 v7, 0xffff0000, v7
	v_fma_f32 v4, v36, v8, v4
	v_fma_f32 v5, v36, v9, v5
	v_fma_f32 v2, v36, v6, v2
	v_fma_f32 v3, v36, v7, v3
.LBB0_757:
	s_and_b64 vcc, exec, s[46:47]
	s_cbranch_vccnz .LBB0_759
	v_mov_b32_e32 v6, v78
	v_mov_b32_e32 v7, v79
	v_lshlrev_b32_e32 v8, 16, v6
	v_and_b32_e32 v9, 0xffff0000, v6
	v_lshlrev_b32_e32 v6, 16, v7
	v_and_b32_e32 v7, 0xffff0000, v7
	v_fma_f32 v4, v18, v8, v4
	v_fma_f32 v5, v18, v9, v5
	v_fma_f32 v2, v18, v6, v2
	v_fma_f32 v3, v18, v7, v3

; __device__ __forceinline__ unsigned cvt_pk_bf16(float lo, float hi) { f32x2_t v = {lo, hi}; bf16x2_t b = __builtin_convertvector(v, bf16x2_t); return __builtin_bit_cast(unsigned, b); }
; __device__ __forceinline__ float bf_lo(unsigned w) { return __uint_as_float(w << 16); }
; __device__ __forceinline__ float bf_hi(unsigned w) { return __uint_as_float(w & 0xffff0000u); }
; __device__ __forceinline__ void moba_own_unit(LAS char* lds, int bh, int jblk, const bf16_t* H, const bf16_t* PO, const float* PML, bf16_t* U, int tid) {
;     ...
; #pragma unroll
;     for (int d0 = 0; d0 < 2; ++d0)
; #pragma unroll
;         for (int g = 0; g < 4; ++g) { const int d = 32 * d0 + 8 * g + 4 * hh; const f32x16& o = d0 ? o1 : o0;
;             float a0 = o[4 * g] * wown, a1 = o[4 * g + 1] * wown, a2 = o[4 * g + 2] * wown, a3 = o[4 * g + 3] * wown;
; #pragma unroll
;             for (int s = 0; s < 3; ++s) if (s < nsel) { const u32x2 pv = *(const u32x2*)(PO + (pidx + s) * 64 + d); a0 += wi[s] * bf_lo(pv.x); a1 += wi[s] * bf_hi(pv.x); a2 += wi[s] * bf_lo(pv.y); a3 += wi[s] * bf_hi(pv.y); }
;             const u32x2 z = zr.z[d0][g];
;             u32x2 w; w.x = cvt_pk_bf16(a0 * inv * bf_lo(z.x), a1 * inv * bf_hi(z.x)); w.y = cvt_pk_bf16(a2 * inv * bf_lo(z.y), a3 * inv * bf_hi(z.y));
;             *(u32x2*)(urow + d) = w; }
.LBB0_761:
	v_mul_f32_e32 v4, v34, v4
	v_mul_f32_e32 v5, v35, v5
	v_lshlrev_b32_e32 v6, 16, v126
	v_and_b32_e32 v7, 0xffff0000, v126
	v_mul_f32_e32 v4, v4, v6
	v_mul_f32_e32 v5, v5, v7
	v_mul_f32_e32 v2, v34, v2
	v_mul_f32_e32 v3, v35, v3
	v_lshlrev_b32_e32 v6, 16, v127
	v_and_b32_e32 v7, 0xffff0000, v127
	v_mul_f32_e32 v2, v2, v6
	v_mul_f32_e32 v3, v3, v7
	v_cvt_pk_bf16_f32 v4, v4, v5
	v_cvt_pk_bf16_f32 v5, v2, v3
	v_mov_b32_e32 v74, v4
	v_mov_b32_e32 v75, v5
	v_mul_f32_e32 v4, v10, v38
	v_mul_f32_e32 v5, v11, v39
	s_and_b64 vcc, exec, s[42:43]
	v_mul_f32_e32 v2, v12, v38
	v_mul_f32_e32 v3, v13, v39
	s_cbranch_vccnz .LBB0_763
	v_mov_b32_e32 v6, v84
	v_mov_b32_e32 v7, v85
	v_lshlrev_b32_e32 v8, 16, v6
	v_and_b32_e32 v9, 0xffff0000, v6
	v_lshlrev_b32_e32 v6, 16, v7
	v_and_b32_e32 v7, 0xffff0000, v7
	v_fma_f32 v4, v36, v8, v4
	v_fma_f32 v5, v36, v9, v5
	v_fma_f32 v2, v36, v6, v2
	v_fma_f32 v3, v36, v7, v3
.LBB0_763:
	s_and_b64 vcc, exec, s[46:47]
	s_cbranch_vccnz .LBB0_765
	v_mov_b32_e32 v6, v88
	v_mov_b32_e32 v7, v89
	v_lshlrev_b32_e32 v8, 16, v6
	v_and_b32_e32 v9, 0xffff0000, v6
	v_lshlrev_b32_e32 v6, 16, v7
	v_and_b32_e32 v7, 0xffff0000, v7
	v_fma_f32 v4, v18, v8, v4
	v_fma_f32 v5, v18, v9, v5
	v_fma_f32 v2, v18, v6, v2
	v_fma_f32 v3, v18, v7, v3
.LBB0_765:
	s_and_b64 vcc, exec, s[48:49]
	s_cbranch_vccnz .LBB0_767
	v_mov_b32_e32 v6, v92
	v_mov_b32_e32 v7, v93
	v_lshlrev_b32_e32 v8, 16, v6
	v_and_b32_e32 v9, 0xffff0000, v6
	v_lshlrev_b32_e32 v6, 16, v7
	v_and_b32_e32 v7, 0xffff0000, v7
	v_fma_f32 v4, v20, v8, v4
	v_fma_f32 v5, v20, v9, v5
	v_fma_f32 v2, v20, v6, v2
	v_fma_f32 v3, v20, v7, v3
.LBB0_767:
	v_mul_f32_e32 v4, v34, v4
	v_mul_f32_e32 v5, v35, v5
	v_lshlrev_b32_e32 v6, 16, v124
	v_and_b32_e32 v7, 0xffff0000, v124
	v_mul_f32_e32 v4, v4, v6
	v_mul_f32_e32 v5, v5, v7
	v_mul_f32_e32 v2, v34, v2
	v_mul_f32_e32 v3, v35, v3
	v_lshlrev_b32_e32 v6, 16, v125
	v_and_b32_e32 v7, 0xffff0000, v125
	v_mul_f32_e32 v2, v2, v6
	v_mul_f32_e32 v3, v3, v7
	v_cvt_pk_bf16_f32 v4, v4, v5
	v_cvt_pk_bf16_f32 v5, v2, v3
	v_mov_b32_e32 v84, v4
	v_mov_b32_e32 v85, v5
	v_mul_f32_e32 v4, v14, v38
	v_mul_f32_e32 v5, v15, v39
	s_and_b64 vcc, exec, s[42:43]
	v_mul_f32_e32 v2, v16, v38
	v_mul_f32_e32 v3, v17, v39
	s_cbranch_vccnz .LBB0_769
	v_mov_b32_e32 v6, v86
	v_mov_b32_e32 v7, v87
	v_lshlrev_b32_e32 v8, 16, v6
	v_and_b32_e32 v9, 0xffff0000, v6
	v_lshlrev_b32_e32 v6, 16, v7
	v_and_b32_e32 v7, 0xffff0000, v7
	v_fma_f32 v4, v36, v8, v4
	v_fma_f32 v5, v36, v9, v5
	v_fma_f32 v2, v36, v6, v2
	v_fma_f32 v3, v36, v7, v3
.LBB0_769:
	s_and_b64 vcc, exec, s[46:47]
	s_cbranch_vccnz .LBB0_771
	v_mov_b32_e32 v6, v90
	v_mov_b32_e32 v7, v91
	v_lshlrev_b32_e32 v8, 16, v6
	v_and_b32_e32 v9, 0xffff0000, v6
	v_lshlrev_b32_e32 v6, 16, v7
	v_and_b32_e32 v7, 0xffff0000, v7
	v_fma_f32 v4, v18, v8, v4
	v_fma_f32 v5, v18, v9, v5
	v_fma_f32 v2, v18, v6, v2
	v_fma_f32 v3, v18, v7, v3
